# PROJN silu and gate epilogues: adjacent f32 mul/add pairs on even register pairs issued as v_pk_mul_f32 / v_pk_add_f32 (constants in s[38:39]); addresses unchanged
# baseline (speedup 1.0000x reference)
.Lepi_projn_g:
	s_mov_b32 s38, 0xbfb8aa3b
	s_mov_b32 s39, 1.0
	s_lshl_b32 s9, s9, 8
	s_add_i32 s9, s9, s60
	s_lshl_b32 s78, s8, 8
	s_or_b32 s78, s78, s26
	s_add_i32 s78, s78, 0xfffffa00
	v_readlane_b32 s68, v255, 32
	v_readlane_b32 s69, v255, 33
	s_lshl_b32 s41, s78, 2
	s_nop 1
	s_add_u32 s68, s68, s41
	s_addc_u32 s69, s69, 0
	v_lshlrev_b32_e32 v131, 2, v176
	global_load_dwordx4 v[132:135], v131, s[68:69] offset:0
	global_load_dwordx4 v[152:155], v131, s[68:69] offset:16
	global_load_dwordx4 v[156:159], v131, s[68:69] offset:512
	global_load_dwordx4 v[160:163], v131, s[68:69] offset:528
	s_cmp_lt_u32 s8, 10
	s_cselect_b32 s41, 0, 0x400
	s_mov_b32 s48, 0x3600000
	s_cselect_b32 s48, s48, 0x7600000
	s_sub_i32 s78, s78, s41
	s_lshl_b32 s78, s78, 1
	s_lshl_b32 s9, s9, 11
	s_add_i32 s9, s9, s78
	s_add_u32 s46, s36, s9
	s_addc_u32 s47, s37, 0
	s_add_u32 s46, s46, s48
	s_addc_u32 s47, s47, 0
	v_lshlrev_b32_e32 v130, 11, v1
	v_lshl_add_u32 v130, v176, 1, v130
	s_waitcnt vmcnt(0)
	v_pk_add_f32 v[164:165], v[126:127], v[132:133]
	v_pk_add_f32 v[166:167], v[128:129], v[134:135]
	v_pk_add_f32 v[168:169], v[122:123], v[152:153]
	v_pk_add_f32 v[170:171], v[124:125], v[154:155]
	v_pk_mul_f32 v[164:165], v[164:165], s[38:39] op_sel_hi:[1,0]
	v_pk_mul_f32 v[166:167], v[166:167], s[38:39] op_sel_hi:[1,0]
	v_pk_mul_f32 v[168:169], v[168:169], s[38:39] op_sel_hi:[1,0]
	v_pk_mul_f32 v[170:171], v[170:171], s[38:39] op_sel_hi:[1,0]
	v_exp_f32_e32 v164, v164
	v_exp_f32_e32 v165, v165
	v_exp_f32_e32 v166, v166
	v_exp_f32_e32 v167, v167
	v_exp_f32_e32 v168, v168
	v_exp_f32_e32 v169, v169
	v_exp_f32_e32 v170, v170
	v_exp_f32_e32 v171, v171
	v_pk_add_f32 v[164:165], v[164:165], s[38:39] op_sel:[0,1] op_sel_hi:[1,1]
	v_pk_add_f32 v[166:167], v[166:167], s[38:39] op_sel:[0,1] op_sel_hi:[1,1]
	v_pk_add_f32 v[168:169], v[168:169], s[38:39] op_sel:[0,1] op_sel_hi:[1,1]
	v_pk_add_f32 v[170:171], v[170:171], s[38:39] op_sel:[0,1] op_sel_hi:[1,1]
	v_rcp_f32_e32 v164, v164
	v_rcp_f32_e32 v165, v165
	v_rcp_f32_e32 v166, v166
	v_rcp_f32_e32 v167, v167
	v_rcp_f32_e32 v168, v168
	v_rcp_f32_e32 v169, v169
	v_rcp_f32_e32 v170, v170
	v_rcp_f32_e32 v171, v171
	v_cvt_pk_bf16_f32 v172, v164, v165
	v_cvt_pk_bf16_f32 v173, v166, v167
	v_cvt_pk_bf16_f32 v174, v168, v169
	v_cvt_pk_bf16_f32 v175, v170, v171
	global_store_dwordx4 v130, v[172:175], s[46:47] nt
	v_pk_add_f32 v[180:181], v[118:119], v[156:157]
	v_pk_add_f32 v[182:183], v[120:121], v[158:159]
	v_pk_add_f32 v[184:185], v[114:115], v[160:161]
	v_pk_add_f32 v[186:187], v[116:117], v[162:163]
	v_pk_mul_f32 v[180:181], v[180:181], s[38:39] op_sel_hi:[1,0]
	v_pk_mul_f32 v[182:183], v[182:183], s[38:39] op_sel_hi:[1,0]
	v_pk_mul_f32 v[184:185], v[184:185], s[38:39] op_sel_hi:[1,0]
	v_pk_mul_f32 v[186:187], v[186:187], s[38:39] op_sel_hi:[1,0]
	v_exp_f32_e32 v180, v180
	v_exp_f32_e32 v181, v181
	v_exp_f32_e32 v182, v182
	v_exp_f32_e32 v183, v183
	v_exp_f32_e32 v184, v184
	v_exp_f32_e32 v185, v185
	v_exp_f32_e32 v186, v186
	v_exp_f32_e32 v187, v187
	v_pk_add_f32 v[180:181], v[180:181], s[38:39] op_sel:[0,1] op_sel_hi:[1,1]
	v_pk_add_f32 v[182:183], v[182:183], s[38:39] op_sel:[0,1] op_sel_hi:[1,1]
	v_pk_add_f32 v[184:185], v[184:185], s[38:39] op_sel:[0,1] op_sel_hi:[1,1]
	v_pk_add_f32 v[186:187], v[186:187], s[38:39] op_sel:[0,1] op_sel_hi:[1,1]
	v_rcp_f32_e32 v180, v180
	v_rcp_f32_e32 v181, v181
	v_rcp_f32_e32 v182, v182
	v_rcp_f32_e32 v183, v183
	v_rcp_f32_e32 v184, v184
	v_rcp_f32_e32 v185, v185
	v_rcp_f32_e32 v186, v186
	v_rcp_f32_e32 v187, v187
	v_cvt_pk_bf16_f32 v188, v180, v181
	v_cvt_pk_bf16_f32 v189, v182, v183
	v_cvt_pk_bf16_f32 v190, v184, v185
	v_cvt_pk_bf16_f32 v191, v186, v187
	global_store_dwordx4 v130, v[188:191], s[46:47] offset:256 nt
	v_pk_add_f32 v[164:165], v[110:111], v[132:133]
	v_pk_add_f32 v[166:167], v[112:113], v[134:135]
	v_pk_add_f32 v[168:169], v[106:107], v[152:153]
	v_pk_add_f32 v[170:171], v[108:109], v[154:155]
	v_pk_mul_f32 v[164:165], v[164:165], s[38:39] op_sel_hi:[1,0]
	v_pk_mul_f32 v[166:167], v[166:167], s[38:39] op_sel_hi:[1,0]
	v_pk_mul_f32 v[168:169], v[168:169], s[38:39] op_sel_hi:[1,0]
	v_pk_mul_f32 v[170:171], v[170:171], s[38:39] op_sel_hi:[1,0]
	v_exp_f32_e32 v164, v164
	v_exp_f32_e32 v165, v165
	v_exp_f32_e32 v166, v166
	v_exp_f32_e32 v167, v167
	v_exp_f32_e32 v168, v168
	v_exp_f32_e32 v169, v169
	v_exp_f32_e32 v170, v170
	v_exp_f32_e32 v171, v171
	v_pk_add_f32 v[164:165], v[164:165], s[38:39] op_sel:[0,1] op_sel_hi:[1,1]
	v_pk_add_f32 v[166:167], v[166:167], s[38:39] op_sel:[0,1] op_sel_hi:[1,1]
	v_pk_add_f32 v[168:169], v[168:169], s[38:39] op_sel:[0,1] op_sel_hi:[1,1]
	v_pk_add_f32 v[170:171], v[170:171], s[38:39] op_sel:[0,1] op_sel_hi:[1,1]
	v_rcp_f32_e32 v164, v164
	v_rcp_f32_e32 v165, v165
	v_rcp_f32_e32 v166, v166
	v_rcp_f32_e32 v167, v167
	v_rcp_f32_e32 v168, v168
	v_rcp_f32_e32 v169, v169
	v_rcp_f32_e32 v170, v170
	v_rcp_f32_e32 v171, v171
	v_cvt_pk_bf16_f32 v172, v164, v165
	v_cvt_pk_bf16_f32 v173, v166, v167
	v_cvt_pk_bf16_f32 v174, v168, v169
	v_cvt_pk_bf16_f32 v175, v170, v171
	s_add_u32 s46, s46, 0x8000
	s_addc_u32 s47, s47, 0
	global_store_dwordx4 v130, v[172:175], s[46:47] nt
	v_pk_add_f32 v[180:181], v[102:103], v[156:157]
	v_pk_add_f32 v[182:183], v[104:105], v[158:159]
	v_pk_add_f32 v[184:185], v[98:99], v[160:161]
	v_pk_add_f32 v[186:187], v[100:101], v[162:163]
	v_pk_mul_f32 v[180:181], v[180:181], s[38:39] op_sel_hi:[1,0]
	v_pk_mul_f32 v[182:183], v[182:183], s[38:39] op_sel_hi:[1,0]
	v_pk_mul_f32 v[184:185], v[184:185], s[38:39] op_sel_hi:[1,0]
	v_pk_mul_f32 v[186:187], v[186:187], s[38:39] op_sel_hi:[1,0]
	v_exp_f32_e32 v180, v180
	v_exp_f32_e32 v181, v181
	v_exp_f32_e32 v182, v182
	v_exp_f32_e32 v183, v183
	v_exp_f32_e32 v184, v184
	v_exp_f32_e32 v185, v185
	v_exp_f32_e32 v186, v186
	v_exp_f32_e32 v187, v187
	v_pk_add_f32 v[180:181], v[180:181], s[38:39] op_sel:[0,1] op_sel_hi:[1,1]
	v_pk_add_f32 v[182:183], v[182:183], s[38:39] op_sel:[0,1] op_sel_hi:[1,1]
	v_pk_add_f32 v[184:185], v[184:185], s[38:39] op_sel:[0,1] op_sel_hi:[1,1]
	v_pk_add_f32 v[186:187], v[186:187], s[38:39] op_sel:[0,1] op_sel_hi:[1,1]
	v_rcp_f32_e32 v180, v180
	v_rcp_f32_e32 v181, v181
	v_rcp_f32_e32 v182, v182
	v_rcp_f32_e32 v183, v183
	v_rcp_f32_e32 v184, v184
	v_rcp_f32_e32 v185, v185
	v_rcp_f32_e32 v186, v186
	v_rcp_f32_e32 v187, v187
	v_cvt_pk_bf16_f32 v188, v180, v181
	v_cvt_pk_bf16_f32 v189, v182, v183
	v_cvt_pk_bf16_f32 v190, v184, v185
	v_cvt_pk_bf16_f32 v191, v186, v187
	global_store_dwordx4 v130, v[188:191], s[46:47] offset:256 nt
	v_pk_add_f32 v[164:165], v[94:95], v[132:133]
	v_pk_add_f32 v[166:167], v[96:97], v[134:135]
	v_pk_add_f32 v[168:169], v[90:91], v[152:153]
	v_pk_add_f32 v[170:171], v[92:93], v[154:155]
	v_pk_mul_f32 v[164:165], v[164:165], s[38:39] op_sel_hi:[1,0]
	v_pk_mul_f32 v[166:167], v[166:167], s[38:39] op_sel_hi:[1,0]
	v_pk_mul_f32 v[168:169], v[168:169], s[38:39] op_sel_hi:[1,0]
	v_pk_mul_f32 v[170:171], v[170:171], s[38:39] op_sel_hi:[1,0]
	v_exp_f32_e32 v164, v164
	v_exp_f32_e32 v165, v165
	v_exp_f32_e32 v166, v166
	v_exp_f32_e32 v167, v167
	v_exp_f32_e32 v168, v168
	v_exp_f32_e32 v169, v169
	v_exp_f32_e32 v170, v170
	v_exp_f32_e32 v171, v171
	v_pk_add_f32 v[164:165], v[164:165], s[38:39] op_sel:[0,1] op_sel_hi:[1,1]
	v_pk_add_f32 v[166:167], v[166:167], s[38:39] op_sel:[0,1] op_sel_hi:[1,1]
	v_pk_add_f32 v[168:169], v[168:169], s[38:39] op_sel:[0,1] op_sel_hi:[1,1]
	v_pk_add_f32 v[170:171], v[170:171], s[38:39] op_sel:[0,1] op_sel_hi:[1,1]
	v_rcp_f32_e32 v164, v164
	v_rcp_f32_e32 v165, v165
	v_rcp_f32_e32 v166, v166
	v_rcp_f32_e32 v167, v167
	v_rcp_f32_e32 v168, v168
	v_rcp_f32_e32 v169, v169
	v_rcp_f32_e32 v170, v170
	v_rcp_f32_e32 v171, v171
	v_cvt_pk_bf16_f32 v172, v164, v165
	v_cvt_pk_bf16_f32 v173, v166, v167
	v_cvt_pk_bf16_f32 v174, v168, v169
	v_cvt_pk_bf16_f32 v175, v170, v171
	s_add_u32 s46, s46, 0x8000
	s_addc_u32 s47, s47, 0
	global_store_dwordx4 v130, v[172:175], s[46:47] nt
	v_pk_add_f32 v[180:181], v[86:87], v[156:157]
	v_pk_add_f32 v[182:183], v[88:89], v[158:159]
	v_pk_add_f32 v[184:185], v[82:83], v[160:161]
	v_pk_add_f32 v[186:187], v[84:85], v[162:163]
	v_pk_mul_f32 v[180:181], v[180:181], s[38:39] op_sel_hi:[1,0]
	v_pk_mul_f32 v[182:183], v[182:183], s[38:39] op_sel_hi:[1,0]
	v_pk_mul_f32 v[184:185], v[184:185], s[38:39] op_sel_hi:[1,0]
	v_pk_mul_f32 v[186:187], v[186:187], s[38:39] op_sel_hi:[1,0]
	v_exp_f32_e32 v180, v180
	v_exp_f32_e32 v181, v181
	v_exp_f32_e32 v182, v182
	v_exp_f32_e32 v183, v183
	v_exp_f32_e32 v184, v184
	v_exp_f32_e32 v185, v185
	v_exp_f32_e32 v186, v186
	v_exp_f32_e32 v187, v187
	v_pk_add_f32 v[180:181], v[180:181], s[38:39] op_sel:[0,1] op_sel_hi:[1,1]
	v_pk_add_f32 v[182:183], v[182:183], s[38:39] op_sel:[0,1] op_sel_hi:[1,1]
	v_pk_add_f32 v[184:185], v[184:185], s[38:39] op_sel:[0,1] op_sel_hi:[1,1]
	v_pk_add_f32 v[186:187], v[186:187], s[38:39] op_sel:[0,1] op_sel_hi:[1,1]
	v_rcp_f32_e32 v180, v180
	v_rcp_f32_e32 v181, v181
	v_rcp_f32_e32 v182, v182
	v_rcp_f32_e32 v183, v183
	v_rcp_f32_e32 v184, v184
	v_rcp_f32_e32 v185, v185
	v_rcp_f32_e32 v186, v186
	v_rcp_f32_e32 v187, v187
	v_cvt_pk_bf16_f32 v188, v180, v181
	v_cvt_pk_bf16_f32 v189, v182, v183
	v_cvt_pk_bf16_f32 v190, v184, v185
	v_cvt_pk_bf16_f32 v191, v186, v187
	global_store_dwordx4 v130, v[188:191], s[46:47] offset:256 nt
	v_pk_add_f32 v[164:165], v[78:79], v[132:133]
	v_pk_add_f32 v[166:167], v[80:81], v[134:135]
	v_pk_add_f32 v[168:169], v[74:75], v[152:153]
	v_pk_add_f32 v[170:171], v[76:77], v[154:155]
	v_pk_mul_f32 v[164:165], v[164:165], s[38:39] op_sel_hi:[1,0]
	v_pk_mul_f32 v[166:167], v[166:167], s[38:39] op_sel_hi:[1,0]
	v_pk_mul_f32 v[168:169], v[168:169], s[38:39] op_sel_hi:[1,0]
	v_pk_mul_f32 v[170:171], v[170:171], s[38:39] op_sel_hi:[1,0]
	v_exp_f32_e32 v164, v164
	v_exp_f32_e32 v165, v165
	v_exp_f32_e32 v166, v166
	v_exp_f32_e32 v167, v167
	v_exp_f32_e32 v168, v168
	v_exp_f32_e32 v169, v169
	v_exp_f32_e32 v170, v170
	v_exp_f32_e32 v171, v171
	v_pk_add_f32 v[164:165], v[164:165], s[38:39] op_sel:[0,1] op_sel_hi:[1,1]
	v_pk_add_f32 v[166:167], v[166:167], s[38:39] op_sel:[0,1] op_sel_hi:[1,1]
	v_pk_add_f32 v[168:169], v[168:169], s[38:39] op_sel:[0,1] op_sel_hi:[1,1]
	v_pk_add_f32 v[170:171], v[170:171], s[38:39] op_sel:[0,1] op_sel_hi:[1,1]
	v_rcp_f32_e32 v164, v164
	v_rcp_f32_e32 v165, v165
	v_rcp_f32_e32 v166, v166
	v_rcp_f32_e32 v167, v167
	v_rcp_f32_e32 v168, v168
	v_rcp_f32_e32 v169, v169
	v_rcp_f32_e32 v170, v170
	v_rcp_f32_e32 v171, v171
	v_cvt_pk_bf16_f32 v172, v164, v165
	v_cvt_pk_bf16_f32 v173, v166, v167
	v_cvt_pk_bf16_f32 v174, v168, v169
	v_cvt_pk_bf16_f32 v175, v170, v171
	s_add_u32 s46, s46, 0x8000
	s_addc_u32 s47, s47, 0
	global_store_dwordx4 v130, v[172:175], s[46:47] nt
	v_pk_add_f32 v[180:181], v[70:71], v[156:157]
	v_pk_add_f32 v[182:183], v[72:73], v[158:159]
	v_pk_add_f32 v[184:185], v[66:67], v[160:161]
	v_pk_add_f32 v[186:187], v[68:69], v[162:163]
	v_pk_mul_f32 v[180:181], v[180:181], s[38:39] op_sel_hi:[1,0]
	v_pk_mul_f32 v[182:183], v[182:183], s[38:39] op_sel_hi:[1,0]
	v_pk_mul_f32 v[184:185], v[184:185], s[38:39] op_sel_hi:[1,0]
	v_pk_mul_f32 v[186:187], v[186:187], s[38:39] op_sel_hi:[1,0]
	v_exp_f32_e32 v180, v180
	v_exp_f32_e32 v181, v181
	v_exp_f32_e32 v182, v182
	v_exp_f32_e32 v183, v183
	v_exp_f32_e32 v184, v184
	v_exp_f32_e32 v185, v185
	v_exp_f32_e32 v186, v186
	v_exp_f32_e32 v187, v187
	v_pk_add_f32 v[180:181], v[180:181], s[38:39] op_sel:[0,1] op_sel_hi:[1,1]
	v_pk_add_f32 v[182:183], v[182:183], s[38:39] op_sel:[0,1] op_sel_hi:[1,1]
	v_pk_add_f32 v[184:185], v[184:185], s[38:39] op_sel:[0,1] op_sel_hi:[1,1]
	v_pk_add_f32 v[186:187], v[186:187], s[38:39] op_sel:[0,1] op_sel_hi:[1,1]
	v_rcp_f32_e32 v180, v180
	v_rcp_f32_e32 v181, v181
	v_rcp_f32_e32 v182, v182
	v_rcp_f32_e32 v183, v183
	v_rcp_f32_e32 v184, v184
	v_rcp_f32_e32 v185, v185
	v_rcp_f32_e32 v186, v186
	v_rcp_f32_e32 v187, v187
	v_cvt_pk_bf16_f32 v188, v180, v181
	v_cvt_pk_bf16_f32 v189, v182, v183
	v_cvt_pk_bf16_f32 v190, v184, v185
	v_cvt_pk_bf16_f32 v191, v186, v187
	global_store_dwordx4 v130, v[188:191], s[46:47] offset:256 nt
	v_pk_add_f32 v[164:165], v[62:63], v[132:133]
	v_pk_add_f32 v[166:167], v[64:65], v[134:135]
	v_pk_add_f32 v[168:169], v[58:59], v[152:153]
	v_pk_add_f32 v[170:171], v[60:61], v[154:155]
	v_pk_mul_f32 v[164:165], v[164:165], s[38:39] op_sel_hi:[1,0]
	v_pk_mul_f32 v[166:167], v[166:167], s[38:39] op_sel_hi:[1,0]
	v_pk_mul_f32 v[168:169], v[168:169], s[38:39] op_sel_hi:[1,0]
	v_pk_mul_f32 v[170:171], v[170:171], s[38:39] op_sel_hi:[1,0]
	v_exp_f32_e32 v164, v164
	v_exp_f32_e32 v165, v165
	v_exp_f32_e32 v166, v166
	v_exp_f32_e32 v167, v167
	v_exp_f32_e32 v168, v168
	v_exp_f32_e32 v169, v169
	v_exp_f32_e32 v170, v170
	v_exp_f32_e32 v171, v171
	v_pk_add_f32 v[164:165], v[164:165], s[38:39] op_sel:[0,1] op_sel_hi:[1,1]
	v_pk_add_f32 v[166:167], v[166:167], s[38:39] op_sel:[0,1] op_sel_hi:[1,1]
	v_pk_add_f32 v[168:169], v[168:169], s[38:39] op_sel:[0,1] op_sel_hi:[1,1]
	v_pk_add_f32 v[170:171], v[170:171], s[38:39] op_sel:[0,1] op_sel_hi:[1,1]
	v_rcp_f32_e32 v164, v164
	v_rcp_f32_e32 v165, v165
	v_rcp_f32_e32 v166, v166
	v_rcp_f32_e32 v167, v167
	v_rcp_f32_e32 v168, v168
	v_rcp_f32_e32 v169, v169
	v_rcp_f32_e32 v170, v170
	v_rcp_f32_e32 v171, v171
	v_cvt_pk_bf16_f32 v172, v164, v165
	v_cvt_pk_bf16_f32 v173, v166, v167
	v_cvt_pk_bf16_f32 v174, v168, v169
	v_cvt_pk_bf16_f32 v175, v170, v171
	s_add_u32 s46, s46, 0x28000
	s_addc_u32 s47, s47, 0
	global_store_dwordx4 v130, v[172:175], s[46:47] nt
	v_pk_add_f32 v[180:181], v[54:55], v[156:157]
	v_pk_add_f32 v[182:183], v[56:57], v[158:159]
	v_pk_add_f32 v[184:185], v[50:51], v[160:161]
	v_pk_add_f32 v[186:187], v[52:53], v[162:163]
	v_pk_mul_f32 v[180:181], v[180:181], s[38:39] op_sel_hi:[1,0]
	v_pk_mul_f32 v[182:183], v[182:183], s[38:39] op_sel_hi:[1,0]
	v_pk_mul_f32 v[184:185], v[184:185], s[38:39] op_sel_hi:[1,0]
	v_pk_mul_f32 v[186:187], v[186:187], s[38:39] op_sel_hi:[1,0]
	v_exp_f32_e32 v180, v180
	v_exp_f32_e32 v181, v181
	v_exp_f32_e32 v182, v182
	v_exp_f32_e32 v183, v183
	v_exp_f32_e32 v184, v184
	v_exp_f32_e32 v185, v185
	v_exp_f32_e32 v186, v186
	v_exp_f32_e32 v187, v187
	v_pk_add_f32 v[180:181], v[180:181], s[38:39] op_sel:[0,1] op_sel_hi:[1,1]
	v_pk_add_f32 v[182:183], v[182:183], s[38:39] op_sel:[0,1] op_sel_hi:[1,1]
	v_pk_add_f32 v[184:185], v[184:185], s[38:39] op_sel:[0,1] op_sel_hi:[1,1]
	v_pk_add_f32 v[186:187], v[186:187], s[38:39] op_sel:[0,1] op_sel_hi:[1,1]
	v_rcp_f32_e32 v180, v180
	v_rcp_f32_e32 v181, v181
	v_rcp_f32_e32 v182, v182
	v_rcp_f32_e32 v183, v183
	v_rcp_f32_e32 v184, v184
	v_rcp_f32_e32 v185, v185
	v_rcp_f32_e32 v186, v186
	v_rcp_f32_e32 v187, v187
	v_cvt_pk_bf16_f32 v188, v180, v181
	v_cvt_pk_bf16_f32 v189, v182, v183
	v_cvt_pk_bf16_f32 v190, v184, v185
	v_cvt_pk_bf16_f32 v191, v186, v187
	global_store_dwordx4 v130, v[188:191], s[46:47] offset:256 nt
	v_pk_add_f32 v[164:165], v[46:47], v[132:133]
	v_pk_add_f32 v[166:167], v[48:49], v[134:135]
	v_pk_add_f32 v[168:169], v[42:43], v[152:153]
	v_pk_add_f32 v[170:171], v[44:45], v[154:155]
	v_pk_mul_f32 v[164:165], v[164:165], s[38:39] op_sel_hi:[1,0]
	v_pk_mul_f32 v[166:167], v[166:167], s[38:39] op_sel_hi:[1,0]
	v_pk_mul_f32 v[168:169], v[168:169], s[38:39] op_sel_hi:[1,0]
	v_pk_mul_f32 v[170:171], v[170:171], s[38:39] op_sel_hi:[1,0]
	v_exp_f32_e32 v164, v164
	v_exp_f32_e32 v165, v165
	v_exp_f32_e32 v166, v166
	v_exp_f32_e32 v167, v167
	v_exp_f32_e32 v168, v168
	v_exp_f32_e32 v169, v169
	v_exp_f32_e32 v170, v170
	v_exp_f32_e32 v171, v171
	v_pk_add_f32 v[164:165], v[164:165], s[38:39] op_sel:[0,1] op_sel_hi:[1,1]
	v_pk_add_f32 v[166:167], v[166:167], s[38:39] op_sel:[0,1] op_sel_hi:[1,1]
	v_pk_add_f32 v[168:169], v[168:169], s[38:39] op_sel:[0,1] op_sel_hi:[1,1]
	v_pk_add_f32 v[170:171], v[170:171], s[38:39] op_sel:[0,1] op_sel_hi:[1,1]
	v_rcp_f32_e32 v164, v164
	v_rcp_f32_e32 v165, v165
	v_rcp_f32_e32 v166, v166
	v_rcp_f32_e32 v167, v167
	v_rcp_f32_e32 v168, v168
	v_rcp_f32_e32 v169, v169
	v_rcp_f32_e32 v170, v170
	v_rcp_f32_e32 v171, v171
	v_cvt_pk_bf16_f32 v172, v164, v165
	v_cvt_pk_bf16_f32 v173, v166, v167
	v_cvt_pk_bf16_f32 v174, v168, v169
	v_cvt_pk_bf16_f32 v175, v170, v171
	s_add_u32 s46, s46, 0x8000
	s_addc_u32 s47, s47, 0
	global_store_dwordx4 v130, v[172:175], s[46:47] nt
	v_pk_add_f32 v[180:181], v[38:39], v[156:157]
	v_pk_add_f32 v[182:183], v[40:41], v[158:159]
	v_pk_add_f32 v[184:185], v[34:35], v[160:161]
	v_pk_add_f32 v[186:187], v[36:37], v[162:163]
	v_pk_mul_f32 v[180:181], v[180:181], s[38:39] op_sel_hi:[1,0]
	v_pk_mul_f32 v[182:183], v[182:183], s[38:39] op_sel_hi:[1,0]
	v_pk_mul_f32 v[184:185], v[184:185], s[38:39] op_sel_hi:[1,0]
	v_pk_mul_f32 v[186:187], v[186:187], s[38:39] op_sel_hi:[1,0]
	v_exp_f32_e32 v180, v180
	v_exp_f32_e32 v181, v181
	v_exp_f32_e32 v182, v182
	v_exp_f32_e32 v183, v183
	v_exp_f32_e32 v184, v184
	v_exp_f32_e32 v185, v185
	v_exp_f32_e32 v186, v186
	v_exp_f32_e32 v187, v187
	v_pk_add_f32 v[180:181], v[180:181], s[38:39] op_sel:[0,1] op_sel_hi:[1,1]
	v_pk_add_f32 v[182:183], v[182:183], s[38:39] op_sel:[0,1] op_sel_hi:[1,1]
	v_pk_add_f32 v[184:185], v[184:185], s[38:39] op_sel:[0,1] op_sel_hi:[1,1]
	v_pk_add_f32 v[186:187], v[186:187], s[38:39] op_sel:[0,1] op_sel_hi:[1,1]
	v_rcp_f32_e32 v180, v180
	v_rcp_f32_e32 v181, v181
	v_rcp_f32_e32 v182, v182
	v_rcp_f32_e32 v183, v183
	v_rcp_f32_e32 v184, v184
	v_rcp_f32_e32 v185, v185
	v_rcp_f32_e32 v186, v186
	v_rcp_f32_e32 v187, v187
	v_cvt_pk_bf16_f32 v188, v180, v181
	v_cvt_pk_bf16_f32 v189, v182, v183
	v_cvt_pk_bf16_f32 v190, v184, v185
	v_cvt_pk_bf16_f32 v191, v186, v187
	global_store_dwordx4 v130, v[188:191], s[46:47] offset:256 nt
	v_pk_add_f32 v[164:165], v[30:31], v[132:133]
	v_pk_add_f32 v[166:167], v[32:33], v[134:135]
	v_pk_add_f32 v[168:169], v[26:27], v[152:153]
	v_pk_add_f32 v[170:171], v[28:29], v[154:155]
	v_pk_mul_f32 v[164:165], v[164:165], s[38:39] op_sel_hi:[1,0]
	v_pk_mul_f32 v[166:167], v[166:167], s[38:39] op_sel_hi:[1,0]
	v_pk_mul_f32 v[168:169], v[168:169], s[38:39] op_sel_hi:[1,0]
	v_pk_mul_f32 v[170:171], v[170:171], s[38:39] op_sel_hi:[1,0]
	v_exp_f32_e32 v164, v164
	v_exp_f32_e32 v165, v165
	v_exp_f32_e32 v166, v166
	v_exp_f32_e32 v167, v167
	v_exp_f32_e32 v168, v168
	v_exp_f32_e32 v169, v169
	v_exp_f32_e32 v170, v170
	v_exp_f32_e32 v171, v171
	v_pk_add_f32 v[164:165], v[164:165], s[38:39] op_sel:[0,1] op_sel_hi:[1,1]
	v_pk_add_f32 v[166:167], v[166:167], s[38:39] op_sel:[0,1] op_sel_hi:[1,1]
	v_pk_add_f32 v[168:169], v[168:169], s[38:39] op_sel:[0,1] op_sel_hi:[1,1]
	v_pk_add_f32 v[170:171], v[170:171], s[38:39] op_sel:[0,1] op_sel_hi:[1,1]
	v_rcp_f32_e32 v164, v164
	v_rcp_f32_e32 v165, v165
	v_rcp_f32_e32 v166, v166
	v_rcp_f32_e32 v167, v167
	v_rcp_f32_e32 v168, v168
	v_rcp_f32_e32 v169, v169
	v_rcp_f32_e32 v170, v170
	v_rcp_f32_e32 v171, v171
	v_cvt_pk_bf16_f32 v172, v164, v165
	v_cvt_pk_bf16_f32 v173, v166, v167
	v_cvt_pk_bf16_f32 v174, v168, v169
	v_cvt_pk_bf16_f32 v175, v170, v171
	s_add_u32 s46, s46, 0x8000
	s_addc_u32 s47, s47, 0
	global_store_dwordx4 v130, v[172:175], s[46:47] nt
	v_pk_add_f32 v[180:181], v[22:23], v[156:157]
	v_pk_add_f32 v[182:183], v[24:25], v[158:159]
	v_pk_add_f32 v[184:185], v[18:19], v[160:161]
	v_pk_add_f32 v[186:187], v[20:21], v[162:163]
	v_pk_mul_f32 v[180:181], v[180:181], s[38:39] op_sel_hi:[1,0]
	v_pk_mul_f32 v[182:183], v[182:183], s[38:39] op_sel_hi:[1,0]
	v_pk_mul_f32 v[184:185], v[184:185], s[38:39] op_sel_hi:[1,0]
	v_pk_mul_f32 v[186:187], v[186:187], s[38:39] op_sel_hi:[1,0]
	v_exp_f32_e32 v180, v180
	v_exp_f32_e32 v181, v181
	v_exp_f32_e32 v182, v182
	v_exp_f32_e32 v183, v183
	v_exp_f32_e32 v184, v184
	v_exp_f32_e32 v185, v185
	v_exp_f32_e32 v186, v186
	v_exp_f32_e32 v187, v187
	v_pk_add_f32 v[180:181], v[180:181], s[38:39] op_sel:[0,1] op_sel_hi:[1,1]
	v_pk_add_f32 v[182:183], v[182:183], s[38:39] op_sel:[0,1] op_sel_hi:[1,1]
	v_pk_add_f32 v[184:185], v[184:185], s[38:39] op_sel:[0,1] op_sel_hi:[1,1]
	v_pk_add_f32 v[186:187], v[186:187], s[38:39] op_sel:[0,1] op_sel_hi:[1,1]
	v_rcp_f32_e32 v180, v180
	v_rcp_f32_e32 v181, v181
	v_rcp_f32_e32 v182, v182
	v_rcp_f32_e32 v183, v183
	v_rcp_f32_e32 v184, v184
	v_rcp_f32_e32 v185, v185
	v_rcp_f32_e32 v186, v186
	v_rcp_f32_e32 v187, v187
	v_cvt_pk_bf16_f32 v188, v180, v181
	v_cvt_pk_bf16_f32 v189, v182, v183
	v_cvt_pk_bf16_f32 v190, v184, v185
	v_cvt_pk_bf16_f32 v191, v186, v187
	global_store_dwordx4 v130, v[188:191], s[46:47] offset:256 nt
	v_pk_add_f32 v[164:165], v[14:15], v[132:133]
	v_pk_add_f32 v[166:167], v[16:17], v[134:135]
	v_pk_add_f32 v[168:169], v[10:11], v[152:153]
	v_pk_add_f32 v[170:171], v[12:13], v[154:155]
	v_pk_mul_f32 v[164:165], v[164:165], s[38:39] op_sel_hi:[1,0]
	v_pk_mul_f32 v[166:167], v[166:167], s[38:39] op_sel_hi:[1,0]
	v_pk_mul_f32 v[168:169], v[168:169], s[38:39] op_sel_hi:[1,0]
	v_pk_mul_f32 v[170:171], v[170:171], s[38:39] op_sel_hi:[1,0]
	v_exp_f32_e32 v164, v164
	v_exp_f32_e32 v165, v165
	v_exp_f32_e32 v166, v166
	v_exp_f32_e32 v167, v167
	v_exp_f32_e32 v168, v168
	v_exp_f32_e32 v169, v169
	v_exp_f32_e32 v170, v170
	v_exp_f32_e32 v171, v171
	v_pk_add_f32 v[164:165], v[164:165], s[38:39] op_sel:[0,1] op_sel_hi:[1,1]
	v_pk_add_f32 v[166:167], v[166:167], s[38:39] op_sel:[0,1] op_sel_hi:[1,1]
	v_pk_add_f32 v[168:169], v[168:169], s[38:39] op_sel:[0,1] op_sel_hi:[1,1]
	v_pk_add_f32 v[170:171], v[170:171], s[38:39] op_sel:[0,1] op_sel_hi:[1,1]
	v_rcp_f32_e32 v164, v164
	v_rcp_f32_e32 v165, v165
	v_rcp_f32_e32 v166, v166
	v_rcp_f32_e32 v167, v167
	v_rcp_f32_e32 v168, v168
	v_rcp_f32_e32 v169, v169
	v_rcp_f32_e32 v170, v170
	v_rcp_f32_e32 v171, v171
	v_cvt_pk_bf16_f32 v172, v164, v165
	v_cvt_pk_bf16_f32 v173, v166, v167
	v_cvt_pk_bf16_f32 v174, v168, v169
	v_cvt_pk_bf16_f32 v175, v170, v171
	s_add_u32 s46, s46, 0x8000
	s_addc_u32 s47, s47, 0
	global_store_dwordx4 v130, v[172:175], s[46:47] nt
	v_pk_add_f32 v[180:181], v[6:7], v[156:157]
	v_pk_add_f32 v[182:183], v[8:9], v[158:159]
	v_pk_add_f32 v[184:185], v[2:3], v[160:161]
	v_pk_add_f32 v[186:187], v[4:5], v[162:163]
	v_pk_mul_f32 v[180:181], v[180:181], s[38:39] op_sel_hi:[1,0]
	v_pk_mul_f32 v[182:183], v[182:183], s[38:39] op_sel_hi:[1,0]
	v_pk_mul_f32 v[184:185], v[184:185], s[38:39] op_sel_hi:[1,0]
	v_pk_mul_f32 v[186:187], v[186:187], s[38:39] op_sel_hi:[1,0]
	v_exp_f32_e32 v180, v180
	v_exp_f32_e32 v181, v181
	v_exp_f32_e32 v182, v182
	v_exp_f32_e32 v183, v183
	v_exp_f32_e32 v184, v184
	v_exp_f32_e32 v185, v185
	v_exp_f32_e32 v186, v186
	v_exp_f32_e32 v187, v187
	v_pk_add_f32 v[180:181], v[180:181], s[38:39] op_sel:[0,1] op_sel_hi:[1,1]
	v_pk_add_f32 v[182:183], v[182:183], s[38:39] op_sel:[0,1] op_sel_hi:[1,1]
	v_pk_add_f32 v[184:185], v[184:185], s[38:39] op_sel:[0,1] op_sel_hi:[1,1]
	v_pk_add_f32 v[186:187], v[186:187], s[38:39] op_sel:[0,1] op_sel_hi:[1,1]
	v_rcp_f32_e32 v180, v180
	v_rcp_f32_e32 v181, v181
	v_rcp_f32_e32 v182, v182
	v_rcp_f32_e32 v183, v183
	v_rcp_f32_e32 v184, v184
	v_rcp_f32_e32 v185, v185
	v_rcp_f32_e32 v186, v186
	v_rcp_f32_e32 v187, v187
	v_cvt_pk_bf16_f32 v188, v180, v181
	v_cvt_pk_bf16_f32 v189, v182, v183
	v_cvt_pk_bf16_f32 v190, v184, v185
	v_cvt_pk_bf16_f32 v191, v186, v187
	global_store_dwordx4 v130, v[188:191], s[46:47] offset:256 nt
	s_branch .LBB0_1251
	s_nop 0
	s_nop 0
	s_nop 0
	s_nop 0
	s_nop 0
	s_nop 0
	s_nop 0
	s_nop 0
	s_nop 0
	s_nop 0
	s_nop 0
	s_nop 0
	s_nop 0
	s_nop 0
	s_nop 0
	s_nop 0
	s_nop 0
	s_nop 0
	s_nop 0
	s_nop 0
	s_nop 0
	s_nop 0
	s_nop 0
	s_nop 0
	s_nop 0
	s_nop 0
	s_nop 0
	s_nop 0
	s_nop 0
	s_nop 0
	s_nop 0
	s_nop 0
	s_nop 0
	s_nop 0
	s_nop 0
	s_nop 0
	s_nop 0
	s_nop 0
	s_nop 0
	s_nop 0
	s_nop 0
	s_nop 0
	s_nop 0
	s_nop 0
	s_nop 0
	s_nop 0
	s_nop 0
	s_nop 0
	s_nop 0
	s_nop 0
	s_nop 0
	s_nop 0
	s_nop 0
	s_nop 0
	s_nop 0
	s_nop 0
	s_nop 0
	s_nop 0
	s_nop 0
	s_nop 0
	s_nop 0
	s_nop 0
	s_nop 0
	s_nop 0
	s_nop 0
	s_nop 0
	s_nop 0
	s_nop 0
	s_nop 0
	s_nop 0
	s_nop 0
	s_nop 0
	s_nop 0
	s_nop 0
	s_nop 0
	s_nop 0
	s_nop 0
	s_nop 0
	s_nop 0
	s_nop 0
	s_nop 0
	s_nop 0
	s_nop 0
	s_nop 0
	s_nop 0
	s_nop 0
	s_nop 0
	s_nop 0
	s_nop 0
	s_nop 0
	s_nop 0
	s_nop 0
	s_nop 0
	s_nop 0
	s_nop 0
	s_nop 0
	s_nop 0
	s_nop 0
	s_nop 0
	s_nop 0
	s_nop 0
	s_nop 0
	s_nop 0
	s_nop 0
	s_nop 0
	s_nop 0
	s_nop 0
	s_nop 0
	s_nop 0
	s_nop 0
	s_nop 0
	s_nop 0
	s_nop 0
	s_nop 0
	s_nop 0
	s_nop 0
	s_nop 0
	s_nop 0
	s_nop 0
	s_nop 0
	s_nop 0
	s_nop 0
	s_nop 0
	s_nop 0
	s_nop 0

.Lepi_projn_silu:
	s_mov_b32 s38, 0xbfb8aa3b
	s_mov_b32 s39, 1.0
	s_lshl_b32 s9, s9, 8
	s_add_i32 s9, s9, s60
	s_lshl_b32 s78, s8, 8
	s_or_b32 s78, s78, s26
	s_add_i32 s78, s78, 0xfffffe00
	s_lshl_b32 s9, s9, 11
	s_lshl_b32 s78, s78, 1
	s_add_i32 s9, s9, s78
	s_add_u32 s46, s36, s9
	s_addc_u32 s47, s37, 0
	s_add_u32 s46, s46, 0xb600000
	s_addc_u32 s47, s47, 0
	v_lshlrev_b32_e32 v130, 11, v1
	v_lshl_add_u32 v130, v176, 1, v130
	v_pk_mul_f32 v[152:153], v[126:127], s[38:39] op_sel_hi:[1,0]
	v_pk_mul_f32 v[154:155], v[128:129], s[38:39] op_sel_hi:[1,0]
	v_pk_mul_f32 v[156:157], v[122:123], s[38:39] op_sel_hi:[1,0]
	v_pk_mul_f32 v[158:159], v[124:125], s[38:39] op_sel_hi:[1,0]
	v_exp_f32_e32 v152, v152
	v_exp_f32_e32 v153, v153
	v_exp_f32_e32 v154, v154
	v_exp_f32_e32 v155, v155
	v_exp_f32_e32 v156, v156
	v_exp_f32_e32 v157, v157
	v_exp_f32_e32 v158, v158
	v_exp_f32_e32 v159, v159
	v_pk_add_f32 v[152:153], v[152:153], s[38:39] op_sel:[0,1] op_sel_hi:[1,1]
	v_pk_add_f32 v[154:155], v[154:155], s[38:39] op_sel:[0,1] op_sel_hi:[1,1]
	v_pk_add_f32 v[156:157], v[156:157], s[38:39] op_sel:[0,1] op_sel_hi:[1,1]
	v_pk_add_f32 v[158:159], v[158:159], s[38:39] op_sel:[0,1] op_sel_hi:[1,1]
	v_rcp_f32_e32 v152, v152
	v_rcp_f32_e32 v153, v153
	v_rcp_f32_e32 v154, v154
	v_rcp_f32_e32 v155, v155
	v_rcp_f32_e32 v156, v156
	v_rcp_f32_e32 v157, v157
	v_rcp_f32_e32 v158, v158
	v_rcp_f32_e32 v159, v159
	v_pk_mul_f32 v[152:153], v[126:127], v[152:153]
	v_pk_mul_f32 v[154:155], v[128:129], v[154:155]
	v_pk_mul_f32 v[156:157], v[122:123], v[156:157]
	v_pk_mul_f32 v[158:159], v[124:125], v[158:159]
	v_cvt_pk_bf16_f32 v132, v152, v153
	v_cvt_pk_bf16_f32 v133, v154, v155
	v_cvt_pk_bf16_f32 v134, v156, v157
	v_cvt_pk_bf16_f32 v135, v158, v159
	global_store_dwordx4 v130, v[132:135], s[46:47] nt
	v_pk_mul_f32 v[160:161], v[118:119], s[38:39] op_sel_hi:[1,0]
	v_pk_mul_f32 v[162:163], v[120:121], s[38:39] op_sel_hi:[1,0]
	v_pk_mul_f32 v[164:165], v[114:115], s[38:39] op_sel_hi:[1,0]
	v_pk_mul_f32 v[166:167], v[116:117], s[38:39] op_sel_hi:[1,0]
	v_exp_f32_e32 v160, v160
	v_exp_f32_e32 v161, v161
	v_exp_f32_e32 v162, v162
	v_exp_f32_e32 v163, v163
	v_exp_f32_e32 v164, v164
	v_exp_f32_e32 v165, v165
	v_exp_f32_e32 v166, v166
	v_exp_f32_e32 v167, v167
	v_pk_add_f32 v[160:161], v[160:161], s[38:39] op_sel:[0,1] op_sel_hi:[1,1]
	v_pk_add_f32 v[162:163], v[162:163], s[38:39] op_sel:[0,1] op_sel_hi:[1,1]
	v_pk_add_f32 v[164:165], v[164:165], s[38:39] op_sel:[0,1] op_sel_hi:[1,1]
	v_pk_add_f32 v[166:167], v[166:167], s[38:39] op_sel:[0,1] op_sel_hi:[1,1]
	v_rcp_f32_e32 v160, v160
	v_rcp_f32_e32 v161, v161
	v_rcp_f32_e32 v162, v162
	v_rcp_f32_e32 v163, v163
	v_rcp_f32_e32 v164, v164
	v_rcp_f32_e32 v165, v165
	v_rcp_f32_e32 v166, v166
	v_rcp_f32_e32 v167, v167
	v_pk_mul_f32 v[160:161], v[118:119], v[160:161]
	v_pk_mul_f32 v[162:163], v[120:121], v[162:163]
	v_pk_mul_f32 v[164:165], v[114:115], v[164:165]
	v_pk_mul_f32 v[166:167], v[116:117], v[166:167]
	v_cvt_pk_bf16_f32 v168, v160, v161
	v_cvt_pk_bf16_f32 v169, v162, v163
	v_cvt_pk_bf16_f32 v170, v164, v165
	v_cvt_pk_bf16_f32 v171, v166, v167
	global_store_dwordx4 v130, v[168:171], s[46:47] offset:256 nt
	v_pk_mul_f32 v[152:153], v[110:111], s[38:39] op_sel_hi:[1,0]
	v_pk_mul_f32 v[154:155], v[112:113], s[38:39] op_sel_hi:[1,0]
	v_pk_mul_f32 v[156:157], v[106:107], s[38:39] op_sel_hi:[1,0]
	v_pk_mul_f32 v[158:159], v[108:109], s[38:39] op_sel_hi:[1,0]
	v_exp_f32_e32 v152, v152
	v_exp_f32_e32 v153, v153
	v_exp_f32_e32 v154, v154
	v_exp_f32_e32 v155, v155
	v_exp_f32_e32 v156, v156
	v_exp_f32_e32 v157, v157
	v_exp_f32_e32 v158, v158
	v_exp_f32_e32 v159, v159
	v_pk_add_f32 v[152:153], v[152:153], s[38:39] op_sel:[0,1] op_sel_hi:[1,1]
	v_pk_add_f32 v[154:155], v[154:155], s[38:39] op_sel:[0,1] op_sel_hi:[1,1]
	v_pk_add_f32 v[156:157], v[156:157], s[38:39] op_sel:[0,1] op_sel_hi:[1,1]
	v_pk_add_f32 v[158:159], v[158:159], s[38:39] op_sel:[0,1] op_sel_hi:[1,1]
	v_rcp_f32_e32 v152, v152
	v_rcp_f32_e32 v153, v153
	v_rcp_f32_e32 v154, v154
	v_rcp_f32_e32 v155, v155
	v_rcp_f32_e32 v156, v156
	v_rcp_f32_e32 v157, v157
	v_rcp_f32_e32 v158, v158
	v_rcp_f32_e32 v159, v159
	v_pk_mul_f32 v[152:153], v[110:111], v[152:153]
	v_pk_mul_f32 v[154:155], v[112:113], v[154:155]
	v_pk_mul_f32 v[156:157], v[106:107], v[156:157]
	v_pk_mul_f32 v[158:159], v[108:109], v[158:159]
	v_cvt_pk_bf16_f32 v132, v152, v153
	v_cvt_pk_bf16_f32 v133, v154, v155
	v_cvt_pk_bf16_f32 v134, v156, v157
	v_cvt_pk_bf16_f32 v135, v158, v159
	s_add_u32 s46, s46, 0x8000
	s_addc_u32 s47, s47, 0
	global_store_dwordx4 v130, v[132:135], s[46:47] nt
	v_pk_mul_f32 v[160:161], v[102:103], s[38:39] op_sel_hi:[1,0]
	v_pk_mul_f32 v[162:163], v[104:105], s[38:39] op_sel_hi:[1,0]
	v_pk_mul_f32 v[164:165], v[98:99], s[38:39] op_sel_hi:[1,0]
	v_pk_mul_f32 v[166:167], v[100:101], s[38:39] op_sel_hi:[1,0]
	v_exp_f32_e32 v160, v160
	v_exp_f32_e32 v161, v161
	v_exp_f32_e32 v162, v162
	v_exp_f32_e32 v163, v163
	v_exp_f32_e32 v164, v164
	v_exp_f32_e32 v165, v165
	v_exp_f32_e32 v166, v166
	v_exp_f32_e32 v167, v167
	v_pk_add_f32 v[160:161], v[160:161], s[38:39] op_sel:[0,1] op_sel_hi:[1,1]
	v_pk_add_f32 v[162:163], v[162:163], s[38:39] op_sel:[0,1] op_sel_hi:[1,1]
	v_pk_add_f32 v[164:165], v[164:165], s[38:39] op_sel:[0,1] op_sel_hi:[1,1]
	v_pk_add_f32 v[166:167], v[166:167], s[38:39] op_sel:[0,1] op_sel_hi:[1,1]
	v_rcp_f32_e32 v160, v160
	v_rcp_f32_e32 v161, v161
	v_rcp_f32_e32 v162, v162
	v_rcp_f32_e32 v163, v163
	v_rcp_f32_e32 v164, v164
	v_rcp_f32_e32 v165, v165
	v_rcp_f32_e32 v166, v166
	v_rcp_f32_e32 v167, v167
	v_pk_mul_f32 v[160:161], v[102:103], v[160:161]
	v_pk_mul_f32 v[162:163], v[104:105], v[162:163]
	v_pk_mul_f32 v[164:165], v[98:99], v[164:165]
	v_pk_mul_f32 v[166:167], v[100:101], v[166:167]
	v_cvt_pk_bf16_f32 v168, v160, v161
	v_cvt_pk_bf16_f32 v169, v162, v163
	v_cvt_pk_bf16_f32 v170, v164, v165
	v_cvt_pk_bf16_f32 v171, v166, v167
	global_store_dwordx4 v130, v[168:171], s[46:47] offset:256 nt
	v_pk_mul_f32 v[152:153], v[94:95], s[38:39] op_sel_hi:[1,0]
	v_pk_mul_f32 v[154:155], v[96:97], s[38:39] op_sel_hi:[1,0]
	v_pk_mul_f32 v[156:157], v[90:91], s[38:39] op_sel_hi:[1,0]
	v_pk_mul_f32 v[158:159], v[92:93], s[38:39] op_sel_hi:[1,0]
	v_exp_f32_e32 v152, v152
	v_exp_f32_e32 v153, v153
	v_exp_f32_e32 v154, v154
	v_exp_f32_e32 v155, v155
	v_exp_f32_e32 v156, v156
	v_exp_f32_e32 v157, v157
	v_exp_f32_e32 v158, v158
	v_exp_f32_e32 v159, v159
	v_pk_add_f32 v[152:153], v[152:153], s[38:39] op_sel:[0,1] op_sel_hi:[1,1]
	v_pk_add_f32 v[154:155], v[154:155], s[38:39] op_sel:[0,1] op_sel_hi:[1,1]
	v_pk_add_f32 v[156:157], v[156:157], s[38:39] op_sel:[0,1] op_sel_hi:[1,1]
	v_pk_add_f32 v[158:159], v[158:159], s[38:39] op_sel:[0,1] op_sel_hi:[1,1]
	v_rcp_f32_e32 v152, v152
	v_rcp_f32_e32 v153, v153
	v_rcp_f32_e32 v154, v154
	v_rcp_f32_e32 v155, v155
	v_rcp_f32_e32 v156, v156
	v_rcp_f32_e32 v157, v157
	v_rcp_f32_e32 v158, v158
	v_rcp_f32_e32 v159, v159
	v_pk_mul_f32 v[152:153], v[94:95], v[152:153]
	v_pk_mul_f32 v[154:155], v[96:97], v[154:155]
	v_pk_mul_f32 v[156:157], v[90:91], v[156:157]
	v_pk_mul_f32 v[158:159], v[92:93], v[158:159]
	v_cvt_pk_bf16_f32 v132, v152, v153
	v_cvt_pk_bf16_f32 v133, v154, v155
	v_cvt_pk_bf16_f32 v134, v156, v157
	v_cvt_pk_bf16_f32 v135, v158, v159
	s_add_u32 s46, s46, 0x8000
	s_addc_u32 s47, s47, 0
	global_store_dwordx4 v130, v[132:135], s[46:47] nt
	v_pk_mul_f32 v[160:161], v[86:87], s[38:39] op_sel_hi:[1,0]
	v_pk_mul_f32 v[162:163], v[88:89], s[38:39] op_sel_hi:[1,0]
	v_pk_mul_f32 v[164:165], v[82:83], s[38:39] op_sel_hi:[1,0]
	v_pk_mul_f32 v[166:167], v[84:85], s[38:39] op_sel_hi:[1,0]
	v_exp_f32_e32 v160, v160
	v_exp_f32_e32 v161, v161
	v_exp_f32_e32 v162, v162
	v_exp_f32_e32 v163, v163
	v_exp_f32_e32 v164, v164
	v_exp_f32_e32 v165, v165
	v_exp_f32_e32 v166, v166
	v_exp_f32_e32 v167, v167
	v_pk_add_f32 v[160:161], v[160:161], s[38:39] op_sel:[0,1] op_sel_hi:[1,1]
	v_pk_add_f32 v[162:163], v[162:163], s[38:39] op_sel:[0,1] op_sel_hi:[1,1]
	v_pk_add_f32 v[164:165], v[164:165], s[38:39] op_sel:[0,1] op_sel_hi:[1,1]
	v_pk_add_f32 v[166:167], v[166:167], s[38:39] op_sel:[0,1] op_sel_hi:[1,1]
	v_rcp_f32_e32 v160, v160
	v_rcp_f32_e32 v161, v161
	v_rcp_f32_e32 v162, v162
	v_rcp_f32_e32 v163, v163
	v_rcp_f32_e32 v164, v164
	v_rcp_f32_e32 v165, v165
	v_rcp_f32_e32 v166, v166
	v_rcp_f32_e32 v167, v167
	v_pk_mul_f32 v[160:161], v[86:87], v[160:161]
	v_pk_mul_f32 v[162:163], v[88:89], v[162:163]
	v_pk_mul_f32 v[164:165], v[82:83], v[164:165]
	v_pk_mul_f32 v[166:167], v[84:85], v[166:167]
	v_cvt_pk_bf16_f32 v168, v160, v161
	v_cvt_pk_bf16_f32 v169, v162, v163
	v_cvt_pk_bf16_f32 v170, v164, v165
	v_cvt_pk_bf16_f32 v171, v166, v167
	global_store_dwordx4 v130, v[168:171], s[46:47] offset:256 nt
	v_pk_mul_f32 v[152:153], v[78:79], s[38:39] op_sel_hi:[1,0]
	v_pk_mul_f32 v[154:155], v[80:81], s[38:39] op_sel_hi:[1,0]
	v_pk_mul_f32 v[156:157], v[74:75], s[38:39] op_sel_hi:[1,0]
	v_pk_mul_f32 v[158:159], v[76:77], s[38:39] op_sel_hi:[1,0]
	v_exp_f32_e32 v152, v152
	v_exp_f32_e32 v153, v153
	v_exp_f32_e32 v154, v154
	v_exp_f32_e32 v155, v155
	v_exp_f32_e32 v156, v156
	v_exp_f32_e32 v157, v157
	v_exp_f32_e32 v158, v158
	v_exp_f32_e32 v159, v159
	v_pk_add_f32 v[152:153], v[152:153], s[38:39] op_sel:[0,1] op_sel_hi:[1,1]
	v_pk_add_f32 v[154:155], v[154:155], s[38:39] op_sel:[0,1] op_sel_hi:[1,1]
	v_pk_add_f32 v[156:157], v[156:157], s[38:39] op_sel:[0,1] op_sel_hi:[1,1]
	v_pk_add_f32 v[158:159], v[158:159], s[38:39] op_sel:[0,1] op_sel_hi:[1,1]
	v_rcp_f32_e32 v152, v152
	v_rcp_f32_e32 v153, v153
	v_rcp_f32_e32 v154, v154
	v_rcp_f32_e32 v155, v155
	v_rcp_f32_e32 v156, v156
	v_rcp_f32_e32 v157, v157
	v_rcp_f32_e32 v158, v158
	v_rcp_f32_e32 v159, v159
	v_pk_mul_f32 v[152:153], v[78:79], v[152:153]
	v_pk_mul_f32 v[154:155], v[80:81], v[154:155]
	v_pk_mul_f32 v[156:157], v[74:75], v[156:157]
	v_pk_mul_f32 v[158:159], v[76:77], v[158:159]
	v_cvt_pk_bf16_f32 v132, v152, v153
	v_cvt_pk_bf16_f32 v133, v154, v155
	v_cvt_pk_bf16_f32 v134, v156, v157
	v_cvt_pk_bf16_f32 v135, v158, v159
	s_add_u32 s46, s46, 0x8000
	s_addc_u32 s47, s47, 0
	global_store_dwordx4 v130, v[132:135], s[46:47] nt
	v_pk_mul_f32 v[160:161], v[70:71], s[38:39] op_sel_hi:[1,0]
	v_pk_mul_f32 v[162:163], v[72:73], s[38:39] op_sel_hi:[1,0]
	v_pk_mul_f32 v[164:165], v[66:67], s[38:39] op_sel_hi:[1,0]
	v_pk_mul_f32 v[166:167], v[68:69], s[38:39] op_sel_hi:[1,0]
	v_exp_f32_e32 v160, v160
	v_exp_f32_e32 v161, v161
	v_exp_f32_e32 v162, v162
	v_exp_f32_e32 v163, v163
	v_exp_f32_e32 v164, v164
	v_exp_f32_e32 v165, v165
	v_exp_f32_e32 v166, v166
	v_exp_f32_e32 v167, v167
	v_pk_add_f32 v[160:161], v[160:161], s[38:39] op_sel:[0,1] op_sel_hi:[1,1]
	v_pk_add_f32 v[162:163], v[162:163], s[38:39] op_sel:[0,1] op_sel_hi:[1,1]
	v_pk_add_f32 v[164:165], v[164:165], s[38:39] op_sel:[0,1] op_sel_hi:[1,1]
	v_pk_add_f32 v[166:167], v[166:167], s[38:39] op_sel:[0,1] op_sel_hi:[1,1]
	v_rcp_f32_e32 v160, v160
	v_rcp_f32_e32 v161, v161
	v_rcp_f32_e32 v162, v162
	v_rcp_f32_e32 v163, v163
	v_rcp_f32_e32 v164, v164
	v_rcp_f32_e32 v165, v165
	v_rcp_f32_e32 v166, v166
	v_rcp_f32_e32 v167, v167
	v_pk_mul_f32 v[160:161], v[70:71], v[160:161]
	v_pk_mul_f32 v[162:163], v[72:73], v[162:163]
	v_pk_mul_f32 v[164:165], v[66:67], v[164:165]
	v_pk_mul_f32 v[166:167], v[68:69], v[166:167]
	v_cvt_pk_bf16_f32 v168, v160, v161
	v_cvt_pk_bf16_f32 v169, v162, v163
	v_cvt_pk_bf16_f32 v170, v164, v165
	v_cvt_pk_bf16_f32 v171, v166, v167
	global_store_dwordx4 v130, v[168:171], s[46:47] offset:256 nt
	v_pk_mul_f32 v[152:153], v[62:63], s[38:39] op_sel_hi:[1,0]
	v_pk_mul_f32 v[154:155], v[64:65], s[38:39] op_sel_hi:[1,0]
	v_pk_mul_f32 v[156:157], v[58:59], s[38:39] op_sel_hi:[1,0]
	v_pk_mul_f32 v[158:159], v[60:61], s[38:39] op_sel_hi:[1,0]
	v_exp_f32_e32 v152, v152
	v_exp_f32_e32 v153, v153
	v_exp_f32_e32 v154, v154
	v_exp_f32_e32 v155, v155
	v_exp_f32_e32 v156, v156
	v_exp_f32_e32 v157, v157
	v_exp_f32_e32 v158, v158
	v_exp_f32_e32 v159, v159
	v_pk_add_f32 v[152:153], v[152:153], s[38:39] op_sel:[0,1] op_sel_hi:[1,1]
	v_pk_add_f32 v[154:155], v[154:155], s[38:39] op_sel:[0,1] op_sel_hi:[1,1]
	v_pk_add_f32 v[156:157], v[156:157], s[38:39] op_sel:[0,1] op_sel_hi:[1,1]
	v_pk_add_f32 v[158:159], v[158:159], s[38:39] op_sel:[0,1] op_sel_hi:[1,1]
	v_rcp_f32_e32 v152, v152
	v_rcp_f32_e32 v153, v153
	v_rcp_f32_e32 v154, v154
	v_rcp_f32_e32 v155, v155
	v_rcp_f32_e32 v156, v156
	v_rcp_f32_e32 v157, v157
	v_rcp_f32_e32 v158, v158
	v_rcp_f32_e32 v159, v159
	v_pk_mul_f32 v[152:153], v[62:63], v[152:153]
	v_pk_mul_f32 v[154:155], v[64:65], v[154:155]
	v_pk_mul_f32 v[156:157], v[58:59], v[156:157]
	v_pk_mul_f32 v[158:159], v[60:61], v[158:159]
	v_cvt_pk_bf16_f32 v132, v152, v153
	v_cvt_pk_bf16_f32 v133, v154, v155
	v_cvt_pk_bf16_f32 v134, v156, v157
	v_cvt_pk_bf16_f32 v135, v158, v159
	s_add_u32 s46, s46, 0x28000
	s_addc_u32 s47, s47, 0
	global_store_dwordx4 v130, v[132:135], s[46:47] nt
	v_pk_mul_f32 v[160:161], v[54:55], s[38:39] op_sel_hi:[1,0]
	v_pk_mul_f32 v[162:163], v[56:57], s[38:39] op_sel_hi:[1,0]
	v_pk_mul_f32 v[164:165], v[50:51], s[38:39] op_sel_hi:[1,0]
	v_pk_mul_f32 v[166:167], v[52:53], s[38:39] op_sel_hi:[1,0]
	v_exp_f32_e32 v160, v160
	v_exp_f32_e32 v161, v161
	v_exp_f32_e32 v162, v162
	v_exp_f32_e32 v163, v163
	v_exp_f32_e32 v164, v164
	v_exp_f32_e32 v165, v165
	v_exp_f32_e32 v166, v166
	v_exp_f32_e32 v167, v167
	v_pk_add_f32 v[160:161], v[160:161], s[38:39] op_sel:[0,1] op_sel_hi:[1,1]
	v_pk_add_f32 v[162:163], v[162:163], s[38:39] op_sel:[0,1] op_sel_hi:[1,1]
	v_pk_add_f32 v[164:165], v[164:165], s[38:39] op_sel:[0,1] op_sel_hi:[1,1]
	v_pk_add_f32 v[166:167], v[166:167], s[38:39] op_sel:[0,1] op_sel_hi:[1,1]
	v_rcp_f32_e32 v160, v160
	v_rcp_f32_e32 v161, v161
	v_rcp_f32_e32 v162, v162
	v_rcp_f32_e32 v163, v163
	v_rcp_f32_e32 v164, v164
	v_rcp_f32_e32 v165, v165
	v_rcp_f32_e32 v166, v166
	v_rcp_f32_e32 v167, v167
	v_pk_mul_f32 v[160:161], v[54:55], v[160:161]
	v_pk_mul_f32 v[162:163], v[56:57], v[162:163]
	v_pk_mul_f32 v[164:165], v[50:51], v[164:165]
	v_pk_mul_f32 v[166:167], v[52:53], v[166:167]
	v_cvt_pk_bf16_f32 v168, v160, v161
	v_cvt_pk_bf16_f32 v169, v162, v163
	v_cvt_pk_bf16_f32 v170, v164, v165
	v_cvt_pk_bf16_f32 v171, v166, v167
	global_store_dwordx4 v130, v[168:171], s[46:47] offset:256 nt
	v_pk_mul_f32 v[152:153], v[46:47], s[38:39] op_sel_hi:[1,0]
	v_pk_mul_f32 v[154:155], v[48:49], s[38:39] op_sel_hi:[1,0]
	v_pk_mul_f32 v[156:157], v[42:43], s[38:39] op_sel_hi:[1,0]
	v_pk_mul_f32 v[158:159], v[44:45], s[38:39] op_sel_hi:[1,0]
	v_exp_f32_e32 v152, v152
	v_exp_f32_e32 v153, v153
	v_exp_f32_e32 v154, v154
	v_exp_f32_e32 v155, v155
	v_exp_f32_e32 v156, v156
	v_exp_f32_e32 v157, v157
	v_exp_f32_e32 v158, v158
	v_exp_f32_e32 v159, v159
	v_pk_add_f32 v[152:153], v[152:153], s[38:39] op_sel:[0,1] op_sel_hi:[1,1]
	v_pk_add_f32 v[154:155], v[154:155], s[38:39] op_sel:[0,1] op_sel_hi:[1,1]
	v_pk_add_f32 v[156:157], v[156:157], s[38:39] op_sel:[0,1] op_sel_hi:[1,1]
	v_pk_add_f32 v[158:159], v[158:159], s[38:39] op_sel:[0,1] op_sel_hi:[1,1]
	v_rcp_f32_e32 v152, v152
	v_rcp_f32_e32 v153, v153
	v_rcp_f32_e32 v154, v154
	v_rcp_f32_e32 v155, v155
	v_rcp_f32_e32 v156, v156
	v_rcp_f32_e32 v157, v157
	v_rcp_f32_e32 v158, v158
	v_rcp_f32_e32 v159, v159
	v_pk_mul_f32 v[152:153], v[46:47], v[152:153]
	v_pk_mul_f32 v[154:155], v[48:49], v[154:155]
	v_pk_mul_f32 v[156:157], v[42:43], v[156:157]
	v_pk_mul_f32 v[158:159], v[44:45], v[158:159]
	v_cvt_pk_bf16_f32 v132, v152, v153
	v_cvt_pk_bf16_f32 v133, v154, v155
	v_cvt_pk_bf16_f32 v134, v156, v157
	v_cvt_pk_bf16_f32 v135, v158, v159
	s_add_u32 s46, s46, 0x8000
	s_addc_u32 s47, s47, 0
	global_store_dwordx4 v130, v[132:135], s[46:47] nt
	v_pk_mul_f32 v[160:161], v[38:39], s[38:39] op_sel_hi:[1,0]
	v_pk_mul_f32 v[162:163], v[40:41], s[38:39] op_sel_hi:[1,0]
	v_pk_mul_f32 v[164:165], v[34:35], s[38:39] op_sel_hi:[1,0]
	v_pk_mul_f32 v[166:167], v[36:37], s[38:39] op_sel_hi:[1,0]
	v_exp_f32_e32 v160, v160
	v_exp_f32_e32 v161, v161
	v_exp_f32_e32 v162, v162
	v_exp_f32_e32 v163, v163
	v_exp_f32_e32 v164, v164
	v_exp_f32_e32 v165, v165
	v_exp_f32_e32 v166, v166
	v_exp_f32_e32 v167, v167
	v_pk_add_f32 v[160:161], v[160:161], s[38:39] op_sel:[0,1] op_sel_hi:[1,1]
	v_pk_add_f32 v[162:163], v[162:163], s[38:39] op_sel:[0,1] op_sel_hi:[1,1]
	v_pk_add_f32 v[164:165], v[164:165], s[38:39] op_sel:[0,1] op_sel_hi:[1,1]
	v_pk_add_f32 v[166:167], v[166:167], s[38:39] op_sel:[0,1] op_sel_hi:[1,1]
	v_rcp_f32_e32 v160, v160
	v_rcp_f32_e32 v161, v161
	v_rcp_f32_e32 v162, v162
	v_rcp_f32_e32 v163, v163
	v_rcp_f32_e32 v164, v164
	v_rcp_f32_e32 v165, v165
	v_rcp_f32_e32 v166, v166
	v_rcp_f32_e32 v167, v167
	v_pk_mul_f32 v[160:161], v[38:39], v[160:161]
	v_pk_mul_f32 v[162:163], v[40:41], v[162:163]
	v_pk_mul_f32 v[164:165], v[34:35], v[164:165]
	v_pk_mul_f32 v[166:167], v[36:37], v[166:167]
	v_cvt_pk_bf16_f32 v168, v160, v161
	v_cvt_pk_bf16_f32 v169, v162, v163
	v_cvt_pk_bf16_f32 v170, v164, v165
	v_cvt_pk_bf16_f32 v171, v166, v167
	global_store_dwordx4 v130, v[168:171], s[46:47] offset:256 nt
	v_pk_mul_f32 v[152:153], v[30:31], s[38:39] op_sel_hi:[1,0]
	v_pk_mul_f32 v[154:155], v[32:33], s[38:39] op_sel_hi:[1,0]
	v_pk_mul_f32 v[156:157], v[26:27], s[38:39] op_sel_hi:[1,0]
	v_pk_mul_f32 v[158:159], v[28:29], s[38:39] op_sel_hi:[1,0]
	v_exp_f32_e32 v152, v152
	v_exp_f32_e32 v153, v153
	v_exp_f32_e32 v154, v154
	v_exp_f32_e32 v155, v155
	v_exp_f32_e32 v156, v156
	v_exp_f32_e32 v157, v157
	v_exp_f32_e32 v158, v158
	v_exp_f32_e32 v159, v159
	v_pk_add_f32 v[152:153], v[152:153], s[38:39] op_sel:[0,1] op_sel_hi:[1,1]
	v_pk_add_f32 v[154:155], v[154:155], s[38:39] op_sel:[0,1] op_sel_hi:[1,1]
	v_pk_add_f32 v[156:157], v[156:157], s[38:39] op_sel:[0,1] op_sel_hi:[1,1]
	v_pk_add_f32 v[158:159], v[158:159], s[38:39] op_sel:[0,1] op_sel_hi:[1,1]
	v_rcp_f32_e32 v152, v152
	v_rcp_f32_e32 v153, v153
	v_rcp_f32_e32 v154, v154
	v_rcp_f32_e32 v155, v155
	v_rcp_f32_e32 v156, v156
	v_rcp_f32_e32 v157, v157
	v_rcp_f32_e32 v158, v158
	v_rcp_f32_e32 v159, v159
	v_pk_mul_f32 v[152:153], v[30:31], v[152:153]
	v_pk_mul_f32 v[154:155], v[32:33], v[154:155]
	v_pk_mul_f32 v[156:157], v[26:27], v[156:157]
	v_pk_mul_f32 v[158:159], v[28:29], v[158:159]
	v_cvt_pk_bf16_f32 v132, v152, v153
	v_cvt_pk_bf16_f32 v133, v154, v155
	v_cvt_pk_bf16_f32 v134, v156, v157
	v_cvt_pk_bf16_f32 v135, v158, v159
	s_add_u32 s46, s46, 0x8000
	s_addc_u32 s47, s47, 0
	global_store_dwordx4 v130, v[132:135], s[46:47] nt
	v_pk_mul_f32 v[160:161], v[22:23], s[38:39] op_sel_hi:[1,0]
	v_pk_mul_f32 v[162:163], v[24:25], s[38:39] op_sel_hi:[1,0]
	v_pk_mul_f32 v[164:165], v[18:19], s[38:39] op_sel_hi:[1,0]
	v_pk_mul_f32 v[166:167], v[20:21], s[38:39] op_sel_hi:[1,0]
	v_exp_f32_e32 v160, v160
	v_exp_f32_e32 v161, v161
	v_exp_f32_e32 v162, v162
	v_exp_f32_e32 v163, v163
	v_exp_f32_e32 v164, v164
	v_exp_f32_e32 v165, v165
	v_exp_f32_e32 v166, v166
	v_exp_f32_e32 v167, v167
	v_pk_add_f32 v[160:161], v[160:161], s[38:39] op_sel:[0,1] op_sel_hi:[1,1]
	v_pk_add_f32 v[162:163], v[162:163], s[38:39] op_sel:[0,1] op_sel_hi:[1,1]
	v_pk_add_f32 v[164:165], v[164:165], s[38:39] op_sel:[0,1] op_sel_hi:[1,1]
	v_pk_add_f32 v[166:167], v[166:167], s[38:39] op_sel:[0,1] op_sel_hi:[1,1]
	v_rcp_f32_e32 v160, v160
	v_rcp_f32_e32 v161, v161
	v_rcp_f32_e32 v162, v162
	v_rcp_f32_e32 v163, v163
	v_rcp_f32_e32 v164, v164
	v_rcp_f32_e32 v165, v165
	v_rcp_f32_e32 v166, v166
	v_rcp_f32_e32 v167, v167
	v_pk_mul_f32 v[160:161], v[22:23], v[160:161]
	v_pk_mul_f32 v[162:163], v[24:25], v[162:163]
	v_pk_mul_f32 v[164:165], v[18:19], v[164:165]
	v_pk_mul_f32 v[166:167], v[20:21], v[166:167]
	v_cvt_pk_bf16_f32 v168, v160, v161
	v_cvt_pk_bf16_f32 v169, v162, v163
	v_cvt_pk_bf16_f32 v170, v164, v165
	v_cvt_pk_bf16_f32 v171, v166, v167
	global_store_dwordx4 v130, v[168:171], s[46:47] offset:256 nt
	v_pk_mul_f32 v[152:153], v[14:15], s[38:39] op_sel_hi:[1,0]
	v_pk_mul_f32 v[154:155], v[16:17], s[38:39] op_sel_hi:[1,0]
	v_pk_mul_f32 v[156:157], v[10:11], s[38:39] op_sel_hi:[1,0]
	v_pk_mul_f32 v[158:159], v[12:13], s[38:39] op_sel_hi:[1,0]
	v_exp_f32_e32 v152, v152
	v_exp_f32_e32 v153, v153
	v_exp_f32_e32 v154, v154
	v_exp_f32_e32 v155, v155
	v_exp_f32_e32 v156, v156
	v_exp_f32_e32 v157, v157
	v_exp_f32_e32 v158, v158
	v_exp_f32_e32 v159, v159
	v_pk_add_f32 v[152:153], v[152:153], s[38:39] op_sel:[0,1] op_sel_hi:[1,1]
	v_pk_add_f32 v[154:155], v[154:155], s[38:39] op_sel:[0,1] op_sel_hi:[1,1]
	v_pk_add_f32 v[156:157], v[156:157], s[38:39] op_sel:[0,1] op_sel_hi:[1,1]
	v_pk_add_f32 v[158:159], v[158:159], s[38:39] op_sel:[0,1] op_sel_hi:[1,1]
	v_rcp_f32_e32 v152, v152
	v_rcp_f32_e32 v153, v153
	v_rcp_f32_e32 v154, v154
	v_rcp_f32_e32 v155, v155
	v_rcp_f32_e32 v156, v156
	v_rcp_f32_e32 v157, v157
	v_rcp_f32_e32 v158, v158
	v_rcp_f32_e32 v159, v159
	v_pk_mul_f32 v[152:153], v[14:15], v[152:153]
	v_pk_mul_f32 v[154:155], v[16:17], v[154:155]
	v_pk_mul_f32 v[156:157], v[10:11], v[156:157]
	v_pk_mul_f32 v[158:159], v[12:13], v[158:159]
	v_cvt_pk_bf16_f32 v132, v152, v153
	v_cvt_pk_bf16_f32 v133, v154, v155
	v_cvt_pk_bf16_f32 v134, v156, v157
	v_cvt_pk_bf16_f32 v135, v158, v159
	s_add_u32 s46, s46, 0x8000
	s_addc_u32 s47, s47, 0
	global_store_dwordx4 v130, v[132:135], s[46:47] nt
	v_pk_mul_f32 v[160:161], v[6:7], s[38:39] op_sel_hi:[1,0]
	v_pk_mul_f32 v[162:163], v[8:9], s[38:39] op_sel_hi:[1,0]
	v_pk_mul_f32 v[164:165], v[2:3], s[38:39] op_sel_hi:[1,0]
	v_pk_mul_f32 v[166:167], v[4:5], s[38:39] op_sel_hi:[1,0]
	v_exp_f32_e32 v160, v160
	v_exp_f32_e32 v161, v161
	v_exp_f32_e32 v162, v162
	v_exp_f32_e32 v163, v163
	v_exp_f32_e32 v164, v164
	v_exp_f32_e32 v165, v165
	v_exp_f32_e32 v166, v166
	v_exp_f32_e32 v167, v167
	v_pk_add_f32 v[160:161], v[160:161], s[38:39] op_sel:[0,1] op_sel_hi:[1,1]
	v_pk_add_f32 v[162:163], v[162:163], s[38:39] op_sel:[0,1] op_sel_hi:[1,1]
	v_pk_add_f32 v[164:165], v[164:165], s[38:39] op_sel:[0,1] op_sel_hi:[1,1]
	v_pk_add_f32 v[166:167], v[166:167], s[38:39] op_sel:[0,1] op_sel_hi:[1,1]
	v_rcp_f32_e32 v160, v160
	v_rcp_f32_e32 v161, v161
	v_rcp_f32_e32 v162, v162
	v_rcp_f32_e32 v163, v163
	v_rcp_f32_e32 v164, v164
	v_rcp_f32_e32 v165, v165
	v_rcp_f32_e32 v166, v166
	v_rcp_f32_e32 v167, v167
	v_pk_mul_f32 v[160:161], v[6:7], v[160:161]
	v_pk_mul_f32 v[162:163], v[8:9], v[162:163]
	v_pk_mul_f32 v[164:165], v[2:3], v[164:165]
	v_pk_mul_f32 v[166:167], v[4:5], v[166:167]
	v_cvt_pk_bf16_f32 v168, v160, v161
	v_cvt_pk_bf16_f32 v169, v162, v163
	v_cvt_pk_bf16_f32 v170, v164, v165
	v_cvt_pk_bf16_f32 v171, v166, v167
	global_store_dwordx4 v130, v[168:171], s[46:47] offset:256 nt
	s_branch .LBB0_1251
	s_nop 0
	s_nop 0
	s_nop 0
	s_nop 0
	s_nop 0
	s_nop 0
	s_nop 0
	s_nop 0
	s_nop 0
	s_nop 0
	s_nop 0
	s_nop 0
	s_nop 0
	s_nop 0
	s_nop 0
	s_nop 0
	s_nop 0
	s_nop 0
	s_nop 0
	s_nop 0
	s_nop 0
	s_nop 0
	s_nop 0
	s_nop 0
	s_nop 0
	s_nop 0
	s_nop 0
	s_nop 0
	s_nop 0
	s_nop 0
	s_nop 0
	s_nop 0
	s_nop 0
	s_nop 0
	s_nop 0
	s_nop 0
	s_nop 0
	s_nop 0
	s_nop 0
	s_nop 0
	s_nop 0
	s_nop 0
	s_nop 0
	s_nop 0
	s_nop 0
	s_nop 0
	s_nop 0
	s_nop 0
	s_nop 0
	s_nop 0
	s_nop 0
	s_nop 0
	s_nop 0
	s_nop 0
	s_nop 0
	s_nop 0
	s_nop 0
	s_nop 0
	s_nop 0
	s_nop 0
	s_nop 0
	s_nop 0
	s_nop 0
	s_nop 0
	s_nop 0
	s_nop 0
	s_nop 0
	s_nop 0
	s_nop 0
	s_nop 0
	s_nop 0
	s_nop 0
	s_nop 0
	s_nop 0
	s_nop 0
	s_nop 0
	s_nop 0
	s_nop 0
	s_nop 0
	s_nop 0
	s_nop 0
	s_nop 0
	s_nop 0
	s_nop 0
	s_nop 0
	s_nop 0
	s_nop 0
	s_nop 0
	s_nop 0
	s_nop 0
	s_nop 0
	s_nop 0
	s_nop 0
	s_nop 0
	s_nop 0
	s_nop 0
	s_nop 0
	s_nop 0
	s_nop 0
	s_nop 0
	s_nop 0
	s_nop 0
	s_nop 0
	s_nop 0
	s_nop 0
	s_nop 0
	s_nop 0
	s_nop 0
	s_nop 0
	s_nop 0
	s_nop 0
	s_nop 0
	s_nop 0
	s_nop 0
	s_nop 0
	s_nop 0
	s_nop 0
	s_nop 0
	s_nop 0
	s_nop 0
	s_nop 0
	s_nop 0
	s_nop 0
	s_nop 0
	s_nop 0
